# phase-1 GEMM: the 101 workgroups that own 13 (not 14) tiles start about half a tile later (3 x s_sleep 127), desynchronising epilogue bursts at no critical-path cost
# baseline (speedup 1.0000x reference)
.LBB0_390:
	s_cmpk_lt_i32 s66, 0x9b
	s_cbranch_scc1 .Lp1_noskew
	s_sleep 127
	s_sleep 127
	s_sleep 127
